# strategy 7.4a: one static s_setprio 1 for waves 4-7 before the attention main loop, reset after it
# speedup vs baseline: 1.0037x; 1.0037x over previous
; #define LAS __attribute__((address_space(3)))
; template <int NQB> ...
;     ...
;     LAS bf16x8* qlds = (LAS bf16x8*)((LAS unsigned char*)red + 4096 + h * 12288) + lane;
; #pragma unroll
;     for (int qb = 0; qb < NQB; ++qb)
; #pragma unroll
;         for (int s = 0; s < 6; ++s) qlds[(qb * 6 + s) * 64] = *(const bf16x8*)(Q + (size_t)(qrow0 + 32 * qb + r) * 768 + h * 96 + 16 * s + 8 * hh);
;     f32x16 O[NQB][2]; float mrun[NQB], lrun[NQB];
; #pragma unroll
;     for (int qb = 0; qb < NQB; ++qb) { mrun[qb] = -1e30f; lrun[qb] = 0.f;
; #pragma unroll
;         for (int db = 0; db < 2; ++db)
; #pragma unroll
;             for (int i = 0; i < 16; ++i) O[qb][db][i] = 0.f; }
;     const int pr = (r & 0x13) | ((r & 4) << 1) | ((r & 8) >> 1);
;     const int blk0 = kvrow0 >> 5; (void)pr;
;     const bf16_t* kp = Kn + ((size_t)(blk0 * 8 + h) * 256 + lane) * 8;
;     const bf16_t* krp = Kr + ((size_t)blk0 * 128 + lane) * 8;
;     const bf16_t* vp = VT + ((size_t)(blk0 * 8 + h) * 256 + lane) * 8;
;     bf16x8 Kf[6];
; #pragma unroll
;     for (int s = 0; s < 4; ++s) Kf[s] = *(const bf16x8*)(kp + 512 * s);
;     Kf[4] = *(const bf16x8*)(krp); Kf[5] = *(const bf16x8*)(krp + 512);
.LBB0_83:
	s_or_b64 exec, exec, s[4:5]
	s_waitcnt lgkmcnt(0)
	s_barrier
	ds_read_b32 v0, v133 offset:2048
	s_movk_i32 s1, 0x80
	s_mov_b64 s[4:5], -1
	s_waitcnt lgkmcnt(0)
	s_barrier
	v_cmp_lt_i32_e32 vcc, s1, v0
	v_readfirstlane_b32 s0, v0
	s_cbranch_vccnz .LBB0_78
	s_mul_i32 s1, s81, 0x3000
	s_cmp_lg_u32 s0, 0
	v_add_u32_e32 v194, s1, v129
	s_cbranch_scc0 .LBB0_92
	s_add_i32 s0, s0, -1
	s_ashr_i32 s20, s0, 2
	s_and_b32 s1, s20, -8
	s_or_b32 s4, s1, s58
	s_and_b32 s0, s0, 31
	s_lshl_b32 s1, s4, 11
	s_lshl_b32 s5, s0, 6
	s_or_b32 s1, s1, s5
	v_bitop3_b32 v162, s1, v182, v169 bitop3:0x36
	s_lshl_b32 s21, s0, 1
	v_or_b32_e32 v6, s1, v169
	v_mad_i64_i32 v[4:5], s[0:1], v162, s78, v[126:127]
	global_load_dwordx4 v[8:11], v[4:5], off
	v_bitop3_b32 v160, v6, 32, v182 bitop3:0xde
	v_ashrrev_i32_e32 v163, 31, v162
	v_ashrrev_i32_e32 v161, 31, v160
	v_mov_b32_e32 v195, 0xf149f2ca
	s_mov_b64 s[44:45], 0
	v_mov_b32_e32 v196, 0xf149f2ca
	global_load_dwordx4 v[12:15], v[4:5], off offset:32
	global_load_dwordx4 v[16:19], v[4:5], off offset:64
	global_load_dwordx4 v[20:23], v[4:5], off offset:96
	global_load_dwordx4 v[24:27], v[4:5], off offset:128
	global_load_dwordx4 v[28:31], v[4:5], off offset:160
	v_mad_i64_i32 v[4:5], s[0:1], v160, s78, v[126:127]
	s_lshl_b32 s1, s4, 9
	s_lshl_b32 s0, s4, 6
	s_add_i32 s4, s1, s81
	s_ashr_i32 s5, s4, 31
	s_lshl_b64 s[4:5], s[4:5], 11
	v_mov_b32_e32 v167, s5
	v_or_b32_e32 v166, s4, v128
	s_ashr_i32 s1, s0, 31
	s_lshl_b64 s[0:1], s[0:1], 11
	global_load_dwordx4 v[32:35], v[4:5], off
	global_load_dwordx4 v[36:39], v[4:5], off offset:32
	global_load_dwordx4 v[40:43], v[4:5], off offset:64
	global_load_dwordx4 v[44:47], v[4:5], off offset:96
	global_load_dwordx4 v[48:51], v[4:5], off offset:128
	global_load_dwordx4 v[52:55], v[4:5], off offset:160
	s_waitcnt vmcnt(0)
	ds_write_b128 v194, v[8:11] offset:4096
	ds_write_b128 v194, v[12:15] offset:5120
	ds_write_b128 v194, v[16:19] offset:6144
	ds_write_b128 v194, v[20:23] offset:7168
	ds_write_b128 v194, v[24:27] offset:8192
	ds_write_b128 v194, v[28:31] offset:9216
	ds_write_b128 v194, v[32:35] offset:10240
	ds_write_b128 v194, v[36:39] offset:11264
	ds_write_b128 v194, v[40:43] offset:12288
	ds_write_b128 v194, v[44:47] offset:13312
	ds_write_b128 v194, v[48:51] offset:14336
	ds_write_b128 v194, v[52:55] offset:15360
	v_lshl_add_u64 v[0:1], v[166:167], 1, s[34:35]
	v_lshl_add_u64 v[2:3], v[130:131], 0, s[0:1]
	global_load_dwordx4 v[116:119], v[0:1], off
	global_load_dwordx4 v[112:115], v[0:1], off offset:1024
	global_load_dwordx4 v[108:111], v[0:1], off offset:2048
	global_load_dwordx4 v[104:107], v[0:1], off offset:3072
	global_load_dwordx4 v[100:103], v[2:3], off
	global_load_dwordx4 v[96:99], v[2:3], off offset:1024
	s_lshr_b32 s1, s20, 3
	s_lshl_b32 s4, s1, 9
	s_or_b32 s4, s47, s4
	s_ashr_i32 s5, s4, 31
	s_xor_b32 s0, s21, 63
	s_lshl_b64 s[4:5], s[4:5], 11
	s_add_u32 s4, s54, s4
	s_addc_u32 s5, s55, s5
	s_lshl_b32 s1, s1, 12
	s_add_i32 s20, s59, s1
	s_ashr_i32 s21, s20, 31
	s_lshl_b64 s[20:21], s[20:21], 12
	s_add_u32 s20, s54, s20
	v_mov_b32_e32 v0, 0
	s_addc_u32 s21, s55, s21
	v_mov_b32_e32 v1, v0
	v_mov_b32_e32 v2, v0
	v_mov_b32_e32 v3, v0
	v_mov_b32_e32 v4, v0
	v_mov_b32_e32 v5, v0
	v_mov_b32_e32 v6, v0
	v_mov_b32_e32 v7, v0
	v_mov_b32_e32 v8, v0
	v_mov_b32_e32 v9, v0
	v_mov_b32_e32 v10, v0
	v_mov_b32_e32 v11, v0
	v_mov_b32_e32 v12, v0
	v_mov_b32_e32 v13, v0
	v_mov_b32_e32 v14, v0
	v_mov_b32_e32 v15, v0
	v_mov_b32_e32 v16, v0
	v_mov_b32_e32 v17, v0
	v_mov_b32_e32 v18, v0
	v_mov_b32_e32 v19, v0
	v_mov_b32_e32 v20, v0
	v_mov_b32_e32 v21, v0
	v_mov_b32_e32 v22, v0
	v_mov_b32_e32 v23, v0
	v_mov_b32_e32 v24, v0
	v_mov_b32_e32 v25, v0
	v_mov_b32_e32 v26, v0
	v_mov_b32_e32 v27, v0
	v_mov_b32_e32 v28, v0
	v_mov_b32_e32 v29, v0
	v_mov_b32_e32 v30, v0
	v_mov_b32_e32 v31, v0
	v_mov_b32_e32 v32, v0
	v_mov_b32_e32 v33, v0
	v_mov_b32_e32 v34, v0
	v_mov_b32_e32 v35, v0
	v_mov_b32_e32 v36, v0
	v_mov_b32_e32 v37, v0
	v_mov_b32_e32 v38, v0
	v_mov_b32_e32 v39, v0
	v_mov_b32_e32 v40, v0
	v_mov_b32_e32 v41, v0
	v_mov_b32_e32 v42, v0
	v_mov_b32_e32 v43, v0
	v_mov_b32_e32 v44, v0
	v_mov_b32_e32 v45, v0
	v_mov_b32_e32 v46, v0
	v_mov_b32_e32 v47, v0
	v_mov_b32_e32 v48, v0
	v_mov_b32_e32 v49, v0
	v_mov_b32_e32 v50, v0
	v_mov_b32_e32 v51, v0
	v_mov_b32_e32 v52, v0
	v_mov_b32_e32 v53, v0
	v_mov_b32_e32 v54, v0
	v_mov_b32_e32 v55, v0
	v_mov_b32_e32 v56, v0
	v_mov_b32_e32 v57, v0
	v_mov_b32_e32 v58, v0
	v_mov_b32_e32 v59, v0
	v_mov_b32_e32 v60, v0
	v_mov_b32_e32 v61, v0
	v_mov_b32_e32 v62, v0
	v_mov_b32_e32 v63, v0
	v_mov_b32_e32 v164, v0
	v_mov_b32_e32 v165, v0
	s_cmp_lt_u32 s81, 4
	s_cbranch_scc1 .Lprio_skip
	s_setprio 1
; #define MFMA32(a, b, c) __builtin_amdgcn_mfma_f32_32x32x16_bf16((a), (b), (c), 0, 0, 0)
; __device__ __forceinline__ float max_x32(float x) { float a, b; swap32(x, a, b); return fmaxf(a, b); }
; template <int NQB> ...
;     ...
;     for (int kb = 0; kb < nkb; ++kb) {
;         asm volatile("" ::: "memory");
;         bf16x8 Vf[2][2];
; #pragma unroll
;         for (int db = 0; db < 2; ++db)
; #pragma unroll
;             for (int s2 = 0; s2 < 2; ++s2) Vf[db][s2] = *(const bf16x8*)(vp + (size_t)kb * 16384 + (db * 2 + s2) * 512);
;         bf16x8 Kx[6];
;         { const int kn = (kb + 1 < nkb) ? kb + 1 : kb;
; #pragma unroll
;             for (int s = 0; s < 4; ++s) Kx[s] = *(const bf16x8*)(kp + (size_t)kn * 16384 + 512 * s);
;             Kx[4] = *(const bf16x8*)(krp + (size_t)kn * 1024); Kx[5] = *(const bf16x8*)(krp + (size_t)kn * 1024 + 512); }
; #pragma unroll
;         for (int qb = 0; qb < NQB; ++qb) {
;             f32x16 X;
; #pragma unroll
;             for (int i = 0; i < 16; ++i) X[i] = 0.f;
; #pragma unroll
;             for (int s = 0; s < 6; ++s) X = MFMA32(Kf[s], qlds[(qb * 6 + s) * 64], X);
;             float mx = X[0];
; #pragma unroll
;             for (int i = 1; i < 16; ++i) mx = fmaxf(mx, X[i]);
;             mx = max_x32(mx);
;             const float mnew = fmaxf(mrun[qb], mx), alpha = __builtin_amdgcn_exp2f(mrun[qb] - mnew); mrun[qb] = mnew;
;             float ps = 0.f;
; #pragma unroll
;             for (int i = 0; i < 16; ++i) { X[i] = __builtin_amdgcn_exp2f(X[i] - mnew); ps += X[i]; }
;             lrun[qb] = lrun[qb] * alpha + ps;
; #pragma unroll
;             for (int db = 0; db < 2; ++db)
; #pragma unroll
;                 for (int i = 0; i < 16; ++i) O[qb][db][i] *= alpha;
.Lprio_skip:
.LBB0_86:
	ds_read_b128 v[64:67], v194 offset:4096
	ds_read_b128 v[120:123], v194 offset:5120
	ds_read_b128 v[80:83], v194 offset:10240
	ds_read_b128 v[198:201], v194 offset:11264
	v_mov_b32_e32 v184, v196
	v_mov_b32_e32 v185, v195
	s_waitcnt vmcnt(5) lgkmcnt(3)
	v_mfma_f32_32x32x16_bf16 v[64:79], v[116:119], v[64:67], 0
	s_add_i32 s0, s0, -1
	s_waitcnt lgkmcnt(1)
	v_mfma_f32_32x32x16_bf16 v[80:95], v[116:119], v[80:83], 0
	s_waitcnt vmcnt(4)
	v_mfma_f32_32x32x16_bf16 v[64:79], v[112:115], v[120:123], v[64:79]
	s_waitcnt lgkmcnt(0)
	v_mfma_f32_32x32x16_bf16 v[80:95], v[112:115], v[198:201], v[80:95]
	s_waitcnt vmcnt(3)
	v_mov_b64_e32 v[114:115], v[110:111]
	v_mov_b64_e32 v[112:113], v[108:109]
	ds_read_b128 v[108:111], v194 offset:6144
	ds_read_b128 v[116:119], v194 offset:7168
	s_waitcnt lgkmcnt(1)
	v_mfma_f32_32x32x16_bf16 v[64:79], v[112:115], v[108:111], v[64:79]
	ds_read_b128 v[120:123], v194 offset:12288
	ds_read_b128 v[108:111], v194 offset:13312
	ds_read_b128 v[196:199], v194 offset:9216
	s_waitcnt lgkmcnt(2)
	v_mfma_f32_32x32x16_bf16 v[80:95], v[112:115], v[120:123], v[80:95]
	s_waitcnt vmcnt(0)
	v_mov_b64_e32 v[122:123], v[98:99]
	v_mov_b64_e32 v[120:121], v[96:97]
	v_lshl_add_u64 v[98:99], s[20:21], 0, v[124:125]
	v_lshl_add_u64 v[96:97], s[4:5], 0, v[124:125]
	ds_read_b128 v[112:115], v194 offset:8192
	s_add_u32 s4, s4, 0x800
	s_addc_u32 s5, s5, 0
	v_mfma_f32_32x32x16_bf16 v[64:79], v[104:107], v[116:119], v[64:79]
	v_add_co_u32_e32 v116, vcc, s75, v98
	s_add_u32 s44, s44, 0x8000
	s_nop 0
	v_addc_co_u32_e32 v117, vcc, 0, v99, vcc
	s_addc_u32 s45, s45, 0
	s_add_u32 s20, s20, 0x8000
	s_waitcnt lgkmcnt(2)
	v_mfma_f32_32x32x16_bf16 v[80:95], v[104:107], v[108:111], v[80:95]
	v_add_co_u32_e32 v104, vcc, s76, v98
	s_addc_u32 s21, s21, 0
	s_nop 0
	v_addc_co_u32_e32 v105, vcc, 0, v99, vcc
	v_add_co_u32_e32 v220, vcc, s77, v96
	s_waitcnt lgkmcnt(0)
	v_mfma_f32_32x32x16_bf16 v[64:79], v[100:103], v[112:115], v[64:79]
	v_addc_co_u32_e32 v221, vcc, 0, v97, vcc
	ds_read_b128 v[96:99], v194 offset:14336
	ds_read_b128 v[200:203], v194 offset:15360
	global_load_dwordx4 v[204:207], v[116:117], off
	global_load_dwordx4 v[208:211], v[116:117], off offset:1024
	s_cmp_eq_u32 s0, 0
	s_waitcnt lgkmcnt(1)
	v_mfma_f32_32x32x16_bf16 v[80:95], v[100:103], v[96:99], v[80:95]
	global_load_dwordx4 v[212:215], v[116:117], off offset:2048
	global_load_dwordx4 v[216:219], v[116:117], off offset:3072
	s_nop 0
	global_load_dwordx4 v[116:119], v[104:105], off
	global_load_dwordx4 v[112:115], v[104:105], off offset:1024
	global_load_dwordx4 v[108:111], v[104:105], off offset:2048
	s_nop 0
	global_load_dwordx4 v[104:107], v[104:105], off offset:3072
	s_nop 0
	global_load_dwordx4 v[100:103], v[220:221], off offset:2048
	global_load_dwordx4 v[96:99], v[220:221], off offset:3072
	v_mfma_f32_32x32x16_bf16 v[64:79], v[120:123], v[196:199], v[64:79]
	s_waitcnt lgkmcnt(0)
	v_mfma_f32_32x32x16_bf16 v[80:95], v[120:123], v[200:203], v[80:95]
	s_nop 9
	v_max_f32_e32 v120, v65, v65
	v_max_f32_e32 v121, v64, v64
	v_max_f32_e32 v120, v121, v120
	v_max3_f32 v120, v120, v66, v67
	v_max3_f32 v120, v120, v68, v69
	v_max3_f32 v120, v120, v70, v71
	v_max3_f32 v120, v120, v72, v73
	v_max_f32_e32 v122, v81, v81
	v_max_f32_e32 v123, v80, v80
	v_max_f32_e32 v121, v123, v122
	v_max3_f32 v121, v121, v82, v83
	v_max3_f32 v121, v121, v84, v85
	v_max3_f32 v121, v121, v86, v87
	v_max3_f32 v121, v121, v88, v89
	v_max3_f32 v120, v120, v74, v75
	v_max3_f32 v121, v121, v90, v91
	v_max3_f32 v120, v120, v76, v77
	v_max3_f32 v121, v121, v92, v93
	v_max3_f32 v120, v120, v78, v79
	v_max3_f32 v121, v121, v94, v95
	v_mov_b32_e32 v122, v120
	v_mov_b32_e32 v123, v121
	s_nop 0
	v_permlane32_swap_b32_e32 v120, v122
	v_permlane32_swap_b32_e32 v121, v123
	v_max3_f32 v196, v184, v120, v122
	v_max3_f32 v195, v185, v121, v123
	v_sub_f32_e32 v120, v184, v196
	v_sub_f32_e32 v64, v64, v196
	v_sub_f32_e32 v65, v65, v196
	v_sub_f32_e32 v66, v66, v196
	v_sub_f32_e32 v67, v67, v196
	v_sub_f32_e32 v68, v68, v196
	v_sub_f32_e32 v69, v69, v196
	v_sub_f32_e32 v70, v70, v196
	v_sub_f32_e32 v71, v71, v196
	v_sub_f32_e32 v72, v72, v196
	v_sub_f32_e32 v121, v73, v196
	v_sub_f32_e32 v74, v74, v196
	v_sub_f32_e32 v122, v75, v196
	v_sub_f32_e32 v76, v76, v196
	v_sub_f32_e32 v123, v77, v196
	v_sub_f32_e32 v184, v78, v196
	v_sub_f32_e32 v197, v79, v196
	v_sub_f32_e32 v185, v185, v195
	v_sub_f32_e32 v78, v80, v195
	v_sub_f32_e32 v80, v81, v195
	v_sub_f32_e32 v82, v82, v195
	v_sub_f32_e32 v198, v83, v195
	v_sub_f32_e32 v84, v84, v195
	v_sub_f32_e32 v199, v85, v195
	v_sub_f32_e32 v86, v86, v195
	v_sub_f32_e32 v200, v87, v195
	v_exp_f32_e32 v73, v64
	v_exp_f32_e32 v75, v65
	v_exp_f32_e32 v77, v66
	v_exp_f32_e32 v79, v67
	v_exp_f32_e32 v81, v68
	v_exp_f32_e32 v83, v69
	v_exp_f32_e32 v85, v70
	v_exp_f32_e32 v87, v71
	v_exp_f32_e32 v68, v120
	v_sub_f32_e32 v201, v89, v195
	v_sub_f32_e32 v203, v91, v195
	v_sub_f32_e32 v221, v93, v195
	v_exp_f32_e32 v89, v72
	v_exp_f32_e32 v91, v121
	v_exp_f32_e32 v93, v74
	v_exp_f32_e32 v121, v76
	v_exp_f32_e32 v72, v78
	v_exp_f32_e32 v74, v80
	v_exp_f32_e32 v76, v82
	v_exp_f32_e32 v78, v198
	v_exp_f32_e32 v80, v84
	v_exp_f32_e32 v82, v199
	v_exp_f32_e32 v84, v86
	v_exp_f32_e32 v86, v200
	v_exp_f32_e32 v198, v185
	v_mul_f32_e32 v62, v68, v62
	v_mul_f32_e32 v63, v68, v63
	v_mul_f32_e32 v60, v68, v60
	v_mul_f32_e32 v61, v68, v61
	v_mul_f32_e32 v58, v68, v58
	v_mul_f32_e32 v59, v68, v59
	v_mul_f32_e32 v56, v68, v56
	v_mul_f32_e32 v57, v68, v57
	v_mul_f32_e32 v54, v68, v54
	v_mul_f32_e32 v55, v68, v55
	v_mul_f32_e32 v52, v68, v52
	v_mul_f32_e32 v53, v68, v53
	v_mul_f32_e32 v50, v68, v50
	v_mul_f32_e32 v51, v68, v51
	v_mul_f32_e32 v48, v68, v48
	v_mul_f32_e32 v49, v68, v49
	v_mul_f32_e32 v46, v68, v46
	v_mul_f32_e32 v47, v68, v47
	v_mul_f32_e32 v44, v68, v44
	v_mul_f32_e32 v45, v68, v45
	v_mul_f32_e32 v42, v68, v42
	v_mul_f32_e32 v43, v68, v43
	v_mul_f32_e32 v40, v68, v40
	v_mul_f32_e32 v41, v68, v41
	v_mul_f32_e32 v38, v68, v38
	v_mul_f32_e32 v39, v68, v39
	v_mul_f32_e32 v36, v68, v36
	v_mul_f32_e32 v37, v68, v37
	v_mul_f32_e32 v34, v68, v34
	v_mul_f32_e32 v35, v68, v35
	v_mul_f32_e32 v32, v68, v32
	v_mul_f32_e32 v33, v68, v33
	v_cvt_pk_bf16_f32 v64, v73, v75
	v_cvt_pk_bf16_f32 v65, v77, v79
	v_cvt_pk_bf16_f32 v66, v81, v83
	v_cvt_pk_bf16_f32 v67, v85, v87
	v_mov_b32_e32 v199, v68
	v_cvt_pk_bf16_f32 v68, v72, v74
	s_waitcnt vmcnt(9)
; __device__ __forceinline__ unsigned pkbf(float lo, float hi) { f2_t v = {lo, hi}; return __builtin_bit_cast(unsigned, __builtin_convertvector(v, bf2_t)); }
; #define MFMA32(a, b, c) __builtin_amdgcn_mfma_f32_32x32x16_bf16((a), (b), (c), 0, 0, 0)
; template <int NQB> ...
;     ...
;         bf16x8 Vf[2][2];
; #pragma unroll
;         for (int db = 0; db < 2; ++db)
; #pragma unroll
;             for (int s2 = 0; s2 < 2; ++s2) Vf[db][s2] = *(const bf16x8*)(vp + (size_t)kb * 16384 + (db * 2 + s2) * 512);
;         bf16x8 Kx[6];
;         { const int kn = (kb + 1 < nkb) ? kb + 1 : kb;
; #pragma unroll
;             for (int s = 0; s < 4; ++s) Kx[s] = *(const bf16x8*)(kp + (size_t)kn * 16384 + 512 * s);
;             Kx[4] = *(const bf16x8*)(krp + (size_t)kn * 1024); Kx[5] = *(const bf16x8*)(krp + (size_t)kn * 1024 + 512); }
; #pragma unroll
;         for (int qb = 0; qb < NQB; ++qb) {
;             f32x16 X;
; #pragma unroll
;             for (int i = 0; i < 16; ++i) X[i] = 0.f;
; #pragma unroll
;             for (int s = 0; s < 6; ++s) X = MFMA32(Kf[s], qlds[(qb * 6 + s) * 64], X);
;     ...
;             const float mnew = fmaxf(mrun[qb], mx), alpha = __builtin_amdgcn_exp2f(mrun[qb] - mnew); mrun[qb] = mnew;
;             float ps = 0.f;
; #pragma unroll
;             for (int i = 0; i < 16; ++i) { X[i] = __builtin_amdgcn_exp2f(X[i] - mnew); ps += X[i]; }
;             lrun[qb] = lrun[qb] * alpha + ps;
; #pragma unroll
;             for (int db = 0; db < 2; ++db)
; #pragma unroll
;                 for (int i = 0; i < 16; ++i) O[qb][db][i] *= alpha;
; #pragma unroll
;             for (int s2 = 0; s2 < 2; ++s2) { u32x4 pw; pw.x = pkbf(X[8 * s2], X[8 * s2 + 1]); pw.y = pkbf(X[8 * s2 + 2], X[8 * s2 + 3]); pw.z = pkbf(X[8 * s2 + 4], X[8 * s2 + 5]); pw.w = pkbf(X[8 * s2 + 6], X[8 * s2 + 7]);
;                 const bf16x8 xs = __builtin_bit_cast(bf16x8, pw);
; #pragma unroll
;                 for (int db = 0; db < 2; ++db) O[qb][db] = MFMA32(Vf[db][s2], xs, O[qb][db]); }
	v_mfma_f32_32x32x16_bf16 v[48:63], v[204:207], v[64:67], v[48:63]
	v_cvt_pk_bf16_f32 v69, v76, v78
	v_cvt_pk_bf16_f32 v70, v80, v82
	v_cvt_pk_bf16_f32 v71, v84, v86
	v_mul_f32_e64 v30, v30, v198
	v_mul_f32_e64 v31, v31, v198
	v_mul_f32_e32 v28, v198, v28
	v_mul_f32_e32 v29, v198, v29
	v_mul_f32_e32 v26, v198, v26
	v_mul_f32_e32 v27, v198, v27
	v_mul_f32_e32 v24, v198, v24
	v_mul_f32_e32 v25, v198, v25
	s_waitcnt vmcnt(7)
	v_mfma_f32_32x32x16_bf16 v[32:47], v[212:215], v[64:67], v[32:47]
	v_mul_f32_e64 v22, v22, v198
	v_mul_f32_e64 v23, v23, v198
	v_mul_f32_e64 v20, v20, v198
	v_mul_f32_e64 v21, v21, v198
	v_mul_f32_e64 v18, v18, v198
	v_mul_f32_e64 v19, v19, v198
	v_mul_f32_e32 v16, v198, v16
	v_mul_f32_e32 v17, v198, v17
	v_mul_f32_e32 v14, v198, v14
	v_mul_f32_e32 v15, v198, v15
	v_mul_f32_e32 v12, v198, v12
	v_mul_f32_e32 v13, v198, v13
	v_mul_f32_e32 v10, v198, v10
	v_mul_f32_e32 v11, v198, v11
	v_mul_f32_e32 v8, v198, v8
	v_mul_f32_e32 v9, v198, v9
	v_mul_f32_e32 v6, v198, v6
	v_mul_f32_e32 v7, v198, v7
	v_mul_f32_e32 v4, v198, v4
	v_mul_f32_e32 v5, v198, v5
	v_mul_f32_e32 v2, v198, v2
	v_mul_f32_e32 v3, v198, v3
	v_mul_f32_e32 v0, v198, v0
	v_mul_f32_e32 v1, v198, v1
	v_pk_add_f32 v[72:73], v[72:73], 0 op_sel_hi:[1,0]
	v_mfma_f32_32x32x16_bf16 v[16:31], v[204:207], v[68:71], v[16:31]
	v_add_f32_e64 v72, v74, v72
	v_add_f32_e64 v73, v75, v73
	v_sub_f32_e32 v88, v88, v195
	v_add_f32_e64 v72, v76, v72
	v_add_f32_e64 v73, v77, v73
	v_sub_f32_e32 v202, v90, v195
	v_sub_f32_e32 v220, v92, v195
	v_sub_f32_e32 v222, v94, v195
	v_sub_f32_e32 v223, v95, v195
	v_mfma_f32_32x32x16_bf16 v[0:15], v[212:215], v[68:71], v[0:15]
	v_exp_f32_e32 v95, v122
	v_exp_f32_e32 v123, v123
	v_exp_f32_e32 v69, v184
	v_exp_f32_e32 v71, v197
	v_add_f32_e32 v72, v78, v72
	v_add_f32_e32 v73, v79, v73
	v_exp_f32_e32 v88, v88
	v_exp_f32_e32 v90, v201
	v_exp_f32_e32 v92, v202
	v_exp_f32_e32 v94, v203
	v_exp_f32_e32 v120, v220
	v_exp_f32_e32 v122, v221
	v_exp_f32_e32 v68, v222
	v_exp_f32_e32 v70, v223
	v_add_f32_e32 v72, v80, v72
	v_add_f32_e32 v73, v81, v73
	v_cvt_pk_bf16_f32 v64, v89, v91
	v_add_f32_e32 v72, v82, v72
	v_add_f32_e32 v73, v83, v73
	v_cvt_pk_bf16_f32 v65, v93, v95
	v_add_f32_e32 v72, v84, v72
	v_add_f32_e32 v73, v85, v73
	v_cvt_pk_bf16_f32 v66, v121, v123
	v_cvt_pk_bf16_f32 v67, v69, v71
	v_add_f32_e32 v72, v86, v72
	v_add_f32_e32 v73, v87, v73
	s_nop 0
	v_mfma_f32_32x32x16_bf16 v[48:63], v[208:211], v[64:67], v[48:63]
	v_add_f32_e64 v72, v88, v72
	v_add_f32_e64 v73, v89, v73
	v_add_f32_e64 v72, v90, v72
	v_add_f32_e64 v73, v91, v73
	s_waitcnt vmcnt(6)
	v_mfma_f32_32x32x16_bf16 v[32:47], v[216:219], v[64:67], v[32:47]
	v_cvt_pk_bf16_f32 v64, v88, v90
	v_cvt_pk_bf16_f32 v65, v92, v94
	v_cvt_pk_bf16_f32 v66, v120, v122
	v_cvt_pk_bf16_f32 v67, v68, v70
	s_nop 1
	v_mfma_f32_32x32x16_bf16 v[16:31], v[208:211], v[64:67], v[16:31]
	v_mfma_f32_32x32x16_bf16 v[0:15], v[216:219], v[64:67], v[0:15]
	v_add_f32_e64 v64, v92, v72
	v_add_f32_e64 v65, v93, v73
	v_add_f32_e64 v64, v94, v64
	v_add_f32_e64 v65, v95, v65
	v_add_f32_e64 v64, v120, v64
	v_add_f32_e64 v65, v121, v65
	v_add_f32_e32 v64, v122, v64
	v_add_f32_e32 v65, v123, v65
	s_nop 0
	v_add_f32_e32 v64, v68, v64
	v_add_f32_e32 v65, v69, v65
	s_nop 0
	v_add_f32_e32 v64, v70, v64
	v_add_f32_e32 v65, v71, v65
	s_nop 0
	v_pk_fma_f32 v[164:165], v[164:165], v[198:199], v[64:65]
	s_cbranch_scc0 .LBB0_86
	s_setprio 0
	v_lshl_add_u64 v[64:65], v[166:167], 1, s[56:57]
	v_lshl_add_u64 v[64:65], v[64:65], 0, s[44:45]
	global_load_dwordx4 v[92:95], v[64:65], off
	global_load_dwordx4 v[80:83], v[64:65], off offset:1024
	global_load_dwordx4 v[88:91], v[64:65], off offset:2048
	global_load_dwordx4 v[84:87], v[64:65], off offset:3072
	ds_read_b128 v[64:67], v194 offset:4096
	ds_read_b128 v[120:123], v194 offset:5120
	s_waitcnt vmcnt(9) lgkmcnt(1)
	v_mfma_f32_32x32x16_bf16 v[64:79], v[116:119], v[64:67], 0
	s_waitcnt vmcnt(8) lgkmcnt(0)
	v_mfma_f32_32x32x16_bf16 v[64:79], v[112:115], v[120:123], v[64:79]
	ds_read_b128 v[120:123], v194 offset:6144
	s_waitcnt vmcnt(7) lgkmcnt(0)
	v_mfma_f32_32x32x16_bf16 v[64:79], v[108:111], v[120:123], v[64:79]
	ds_read_b128 v[120:123], v194 offset:7168
	s_waitcnt vmcnt(6) lgkmcnt(0)
	v_mfma_f32_32x32x16_bf16 v[64:79], v[104:107], v[120:123], v[64:79]
	ds_read_b128 v[120:123], v194 offset:8192
	s_waitcnt vmcnt(5) lgkmcnt(0)
	v_mfma_f32_32x32x16_bf16 v[64:79], v[100:103], v[120:123], v[64:79]
	ds_read_b128 v[120:123], v194 offset:9216
	s_waitcnt vmcnt(4) lgkmcnt(0)
; __device__ __forceinline__ unsigned pkbf(float lo, float hi) { f2_t v = {lo, hi}; return __builtin_bit_cast(unsigned, __builtin_convertvector(v, bf2_t)); }
; #define MFMA32(a, b, c) __builtin_amdgcn_mfma_f32_32x32x16_bf16((a), (b), (c), 0, 0, 0)
; __device__ __forceinline__ float max_x32(float x) { float a, b; swap32(x, a, b); return fmaxf(a, b); }
; template <int NQB> ...
;     ...
;             for (int s = 0; s < 6; ++s) X = MFMA32(Kf[s], qlds[(qb * 6 + s) * 64], X);
;             float mx = X[0];
; #pragma unroll
;             for (int i = 1; i < 16; ++i) mx = fmaxf(mx, X[i]);
;             mx = max_x32(mx);
;             const float mnew = fmaxf(mrun[qb], mx), alpha = __builtin_amdgcn_exp2f(mrun[qb] - mnew); mrun[qb] = mnew;
;             float ps = 0.f;
; #pragma unroll
;             for (int i = 0; i < 16; ++i) { X[i] = __builtin_amdgcn_exp2f(X[i] - mnew); ps += X[i]; }
;             lrun[qb] = lrun[qb] * alpha + ps;
; #pragma unroll
;             for (int db = 0; db < 2; ++db)
; #pragma unroll
;                 for (int i = 0; i < 16; ++i) O[qb][db][i] *= alpha;
; #pragma unroll
;             for (int s2 = 0; s2 < 2; ++s2) { u32x4 pw; pw.x = pkbf(X[8 * s2], X[8 * s2 + 1]); pw.y = pkbf(X[8 * s2 + 2], X[8 * s2 + 3]); pw.z = pkbf(X[8 * s2 + 4], X[8 * s2 + 5]); pw.w = pkbf(X[8 * s2 + 6], X[8 * s2 + 7]);
;                 const bf16x8 xs = __builtin_bit_cast(bf16x8, pw);
; #pragma unroll
;                 for (int db = 0; db < 2; ++db) O[qb][db] = MFMA32(Vf[db][s2], xs, O[qb][db]); }
	v_mfma_f32_32x32x16_bf16 v[64:79], v[96:99], v[120:123], v[64:79]
	s_nop 11
	v_max_f32_e32 v120, v65, v65
	v_max_f32_e32 v121, v64, v64
	v_max_f32_e32 v120, v121, v120
	v_max3_f32 v120, v120, v66, v67
	v_max3_f32 v120, v120, v68, v69
	v_max3_f32 v120, v120, v70, v71
	v_max3_f32 v120, v120, v72, v73
	v_max3_f32 v120, v120, v74, v75
	v_max3_f32 v120, v120, v76, v77
	v_max3_f32 v120, v120, v78, v79
	v_mov_b32_e32 v121, v120
	s_nop 1
	v_permlane32_swap_b32_e32 v120, v121
	v_max3_f32 v120, v196, v120, v121
	v_sub_f32_e32 v64, v64, v120
	v_exp_f32_e32 v122, v64
	v_sub_f32_e32 v65, v65, v120
	v_exp_f32_e32 v65, v65
	v_sub_f32_e32 v66, v66, v120
	v_exp_f32_e32 v66, v66
	v_sub_f32_e32 v67, v67, v120
	v_exp_f32_e32 v67, v67
	v_sub_f32_e32 v68, v68, v120
	v_add_f32_e32 v64, 0, v122
	v_exp_f32_e32 v68, v68
	v_sub_f32_e32 v69, v69, v120
	v_add_f32_e32 v64, v65, v64
	v_exp_f32_e32 v69, v69
	v_sub_f32_e32 v70, v70, v120
	v_add_f32_e32 v64, v66, v64
	v_exp_f32_e32 v70, v70
	v_sub_f32_e32 v71, v71, v120
	v_add_f32_e32 v64, v67, v64
	v_exp_f32_e32 v71, v71
	v_sub_f32_e32 v72, v72, v120
	v_add_f32_e32 v64, v68, v64
	v_exp_f32_e32 v72, v72
	v_sub_f32_e32 v73, v73, v120
	v_add_f32_e32 v64, v69, v64
	v_exp_f32_e32 v73, v73
	v_sub_f32_e32 v74, v74, v120
	v_add_f32_e32 v64, v70, v64
	v_exp_f32_e32 v74, v74
	v_sub_f32_e32 v75, v75, v120
	v_add_f32_e32 v64, v71, v64
	v_exp_f32_e32 v75, v75
	v_sub_f32_e32 v76, v76, v120
	v_add_f32_e32 v64, v72, v64
	v_exp_f32_e32 v76, v76
	v_sub_f32_e32 v77, v77, v120
	v_add_f32_e32 v64, v73, v64
	v_exp_f32_e32 v77, v77
	v_sub_f32_e32 v78, v78, v120
	v_add_f32_e32 v64, v74, v64
	v_exp_f32_e32 v78, v78
	v_sub_f32_e32 v79, v79, v120
	v_add_f32_e32 v64, v75, v64
	v_exp_f32_e32 v79, v79
	v_add_f32_e32 v64, v76, v64
	v_add_f32_e32 v64, v77, v64
	v_sub_f32_e32 v121, v196, v120
	v_add_f32_e32 v64, v78, v64
	v_add_f32_e32 v120, v79, v64
	v_exp_f32_e32 v64, v121
	s_nop 0
	v_fmac_f32_e32 v120, v165, v64
	v_pk_mul_f32 v[62:63], v[62:63], v[64:65] op_sel_hi:[1,0]
	v_pk_mul_f32 v[60:61], v[60:61], v[64:65] op_sel_hi:[1,0]
	v_pk_mul_f32 v[58:59], v[58:59], v[64:65] op_sel_hi:[1,0]
	v_pk_mul_f32 v[56:57], v[56:57], v[64:65] op_sel_hi:[1,0]
	v_pk_mul_f32 v[54:55], v[54:55], v[64:65] op_sel_hi:[1,0]
	v_pk_mul_f32 v[52:53], v[52:53], v[64:65] op_sel_hi:[1,0]
	v_pk_mul_f32 v[50:51], v[50:51], v[64:65] op_sel_hi:[1,0]
	v_pk_mul_f32 v[48:49], v[48:49], v[64:65] op_sel_hi:[1,0]
	v_pk_mul_f32 v[46:47], v[46:47], v[64:65] op_sel_hi:[1,0]
	v_pk_mul_f32 v[44:45], v[44:45], v[64:65] op_sel_hi:[1,0]
	v_pk_mul_f32 v[42:43], v[42:43], v[64:65] op_sel_hi:[1,0]
	v_pk_mul_f32 v[40:41], v[40:41], v[64:65] op_sel_hi:[1,0]
	v_pk_mul_f32 v[38:39], v[38:39], v[64:65] op_sel_hi:[1,0]
	v_pk_mul_f32 v[36:37], v[36:37], v[64:65] op_sel_hi:[1,0]
	v_pk_mul_f32 v[34:35], v[34:35], v[64:65] op_sel_hi:[1,0]
	v_pk_mul_f32 v[32:33], v[32:33], v[64:65] op_sel_hi:[1,0]
	v_cvt_pk_bf16_f32 v64, v122, v65
	v_cvt_pk_bf16_f32 v65, v66, v67
	v_cvt_pk_bf16_f32 v66, v68, v69
	v_cvt_pk_bf16_f32 v67, v70, v71
	s_waitcnt vmcnt(3)
	s_nop 0
	v_mfma_f32_32x32x16_bf16 v[48:63], v[92:95], v[64:67], v[48:63]
	s_waitcnt vmcnt(1)
	v_mfma_f32_32x32x16_bf16 v[32:47], v[88:91], v[64:67], v[32:47]
	v_cvt_pk_bf16_f32 v64, v72, v73
	v_cvt_pk_bf16_f32 v65, v74, v75
	v_cvt_pk_bf16_f32 v66, v76, v77
	v_cvt_pk_bf16_f32 v67, v78, v79
	s_nop 1
	v_mfma_f32_32x32x16_bf16 v[48:63], v[80:83], v[64:67], v[48:63]
	s_waitcnt vmcnt(0)
	v_mfma_f32_32x32x16_bf16 v[32:47], v[84:87], v[64:67], v[32:47]
	ds_read_b128 v[64:67], v194 offset:10240
	s_waitcnt lgkmcnt(0)
	v_mfma_f32_32x32x16_bf16 v[64:79], v[116:119], v[64:67], 0
	ds_read_b128 v[116:119], v194 offset:11264
	s_waitcnt lgkmcnt(0)
	v_mfma_f32_32x32x16_bf16 v[64:79], v[112:115], v[116:119], v[64:79]
	ds_read_b128 v[112:115], v194 offset:12288
	s_waitcnt lgkmcnt(0)
	v_mfma_f32_32x32x16_bf16 v[64:79], v[108:111], v[112:115], v[64:79]
	ds_read_b128 v[108:111], v194 offset:13312
	s_waitcnt lgkmcnt(0)
	v_mfma_f32_32x32x16_bf16 v[64:79], v[104:107], v[108:111], v[64:79]
	ds_read_b128 v[104:107], v194 offset:14336
	s_waitcnt lgkmcnt(0)
	v_mfma_f32_32x32x16_bf16 v[64:79], v[100:103], v[104:107], v[64:79]
	ds_read_b128 v[100:103], v194 offset:15360
	s_waitcnt lgkmcnt(0)
	v_mfma_f32_32x32x16_bf16 v[64:79], v[96:99], v[100:103], v[64:79]
	s_nop 11
	v_max_f32_e32 v96, v65, v65
	v_max_f32_e32 v97, v64, v64
	v_max_f32_e32 v96, v97, v96
	v_max3_f32 v96, v96, v66, v67
	v_max3_f32 v96, v96, v68, v69
	v_max3_f32 v96, v96, v70, v71
	v_max3_f32 v96, v96, v72, v73
	v_max3_f32 v96, v96, v74, v75
	v_max3_f32 v96, v96, v76, v77
	v_max3_f32 v96, v96, v78, v79
	v_mov_b32_e32 v97, v96
	s_nop 1
	v_permlane32_swap_b32_e32 v96, v97
	v_max3_f32 v99, v195, v96, v97
	v_sub_f32_e32 v64, v64, v99
	v_exp_f32_e32 v96, v64
	v_sub_f32_e32 v64, v65, v99
	v_exp_f32_e32 v65, v64
	v_sub_f32_e32 v64, v66, v99
	v_exp_f32_e32 v97, v64
	v_sub_f32_e32 v64, v67, v99
	v_exp_f32_e32 v98, v64
	v_sub_f32_e32 v64, v68, v99
	v_exp_f32_e32 v68, v64
	v_sub_f32_e32 v64, v69, v99
	v_exp_f32_e32 v69, v64
	v_sub_f32_e32 v64, v70, v99
	v_exp_f32_e32 v70, v64
	v_sub_f32_e32 v64, v71, v99
	v_exp_f32_e32 v71, v64
	v_sub_f32_e32 v64, v72, v99
	v_exp_f32_e32 v72, v64
	v_sub_f32_e32 v64, v73, v99
	v_exp_f32_e32 v73, v64
	v_sub_f32_e32 v64, v74, v99
	v_exp_f32_e32 v74, v64
	v_sub_f32_e32 v64, v75, v99
	v_exp_f32_e32 v75, v64
	v_sub_f32_e32 v64, v76, v99
	v_exp_f32_e32 v76, v64
	v_sub_f32_e32 v64, v77, v99
	v_exp_f32_e32 v77, v64
	v_sub_f32_e32 v64, v78, v99
	v_sub_f32_e32 v100, v195, v99
	v_exp_f32_e32 v78, v64
	v_sub_f32_e32 v64, v79, v99
	v_exp_f32_e32 v79, v64
	v_exp_f32_e32 v64, v100
	v_cvt_pk_bf16_f32 v100, v96, v65
; __device__ __forceinline__ unsigned pkbf(float lo, float hi) { f2_t v = {lo, hi}; return __builtin_bit_cast(unsigned, __builtin_convertvector(v, bf2_t)); }
; #define MFMA32(a, b, c) __builtin_amdgcn_mfma_f32_32x32x16_bf16((a), (b), (c), 0, 0, 0)
; __device__ __forceinline__ float sum_x32(float x) { float a, b; swap32(x, a, b); return a + b; }
; template <int NQB> ...
;     ...
;             for (int i = 0; i < 16; ++i) { X[i] = __builtin_amdgcn_exp2f(X[i] - mnew); ps += X[i]; }
;             lrun[qb] = lrun[qb] * alpha + ps;
; #pragma unroll
;             for (int db = 0; db < 2; ++db)
; #pragma unroll
;                 for (int i = 0; i < 16; ++i) O[qb][db][i] *= alpha;
; #pragma unroll
;             for (int s2 = 0; s2 < 2; ++s2) { u32x4 pw; pw.x = pkbf(X[8 * s2], X[8 * s2 + 1]); pw.y = pkbf(X[8 * s2 + 2], X[8 * s2 + 3]); pw.z = pkbf(X[8 * s2 + 4], X[8 * s2 + 5]); pw.w = pkbf(X[8 * s2 + 6], X[8 * s2 + 7]);
;                 const bf16x8 xs = __builtin_bit_cast(bf16x8, pw);
; #pragma unroll
;                 for (int db = 0; db < 2; ++db) O[qb][db] = MFMA32(Vf[db][s2], xs, O[qb][db]); }
;         }
; #pragma unroll
;         for (int s = 0; s < 6; ++s) Kf[s] = Kx[s];
;     }
; #pragma unroll
;     for (int qb = 0; qb < NQB; ++qb) { const float lt = sum_x32(lrun[qb]); const float inv = 1.0f / lt; float ss = 0.f;
; #pragma unroll
;         for (int db = 0; db < 2; ++db)
; #pragma unroll
;             for (int i = 0; i < 16; ++i) { O[qb][db][i] *= inv; ss += O[qb][db][i] * O[qb][db][i]; }
;         ss = sum_x32(ss);
;         if (hh == 0) red[h * 64 + qb * 32 + r] = ss; }
	v_cvt_pk_bf16_f32 v101, v97, v98
	v_cvt_pk_bf16_f32 v102, v68, v69
	v_pk_mul_f32 v[30:31], v[30:31], v[64:65] op_sel_hi:[1,0]
	v_pk_mul_f32 v[28:29], v[28:29], v[64:65] op_sel_hi:[1,0]
	v_pk_mul_f32 v[26:27], v[26:27], v[64:65] op_sel_hi:[1,0]
	v_pk_mul_f32 v[24:25], v[24:25], v[64:65] op_sel_hi:[1,0]
	v_pk_mul_f32 v[22:23], v[22:23], v[64:65] op_sel_hi:[1,0]
	v_pk_mul_f32 v[20:21], v[20:21], v[64:65] op_sel_hi:[1,0]
	v_pk_mul_f32 v[18:19], v[18:19], v[64:65] op_sel_hi:[1,0]
	v_pk_mul_f32 v[16:17], v[16:17], v[64:65] op_sel_hi:[1,0]
	v_cvt_pk_bf16_f32 v103, v70, v71
	v_mov_b32_e32 v66, v120
	s_nop 1
	v_permlane32_swap_b32_e32 v120, v66
	v_mfma_f32_32x32x16_bf16 v[16:31], v[92:95], v[100:103], v[16:31]
	v_mul_f32_e64 v14, v14, v64
	v_mul_f32_e64 v15, v15, v64
	v_mul_f32_e64 v12, v12, v64
	v_mul_f32_e64 v13, v13, v64
	v_mul_f32_e64 v10, v10, v64
	v_mul_f32_e64 v11, v11, v64
	v_pk_mul_f32 v[8:9], v[8:9], v[64:65] op_sel_hi:[1,0]
	v_pk_mul_f32 v[6:7], v[6:7], v[64:65] op_sel_hi:[1,0]
	v_pk_mul_f32 v[4:5], v[4:5], v[64:65] op_sel_hi:[1,0]
	v_pk_mul_f32 v[2:3], v[2:3], v[64:65] op_sel_hi:[1,0]
	v_pk_mul_f32 v[0:1], v[0:1], v[64:65] op_sel_hi:[1,0]
	v_add_f32_e32 v66, v120, v66
	v_div_scale_f32 v67, s[0:1], v66, v66, 1.0
	v_mfma_f32_32x32x16_bf16 v[0:15], v[88:91], v[100:103], v[0:15]
	v_cvt_pk_bf16_f32 v88, v72, v73
	v_cvt_pk_bf16_f32 v89, v74, v75
	v_cvt_pk_bf16_f32 v90, v76, v77
	v_cvt_pk_bf16_f32 v91, v78, v79
	s_nop 1
	v_mfma_f32_32x32x16_bf16 v[16:31], v[80:83], v[88:91], v[16:31]
	v_rcp_f32_e32 v80, v67
	s_nop 0
	v_fma_f32 v81, -v67, v80, 1.0
	v_fmac_f32_e32 v80, v81, v80
	v_div_scale_f32 v81, vcc, 1.0, v66, 1.0
	v_mul_f32_e32 v82, v81, v80
	v_fma_f32 v83, -v67, v82, v81
	v_fmac_f32_e32 v82, v83, v80
	v_fma_f32 v67, -v67, v82, v81
	v_div_fmas_f32 v67, v67, v80, v82
	v_div_fixup_f32 v80, v67, v66, 1.0
	v_pk_mul_f32 v[48:49], v[48:49], v[80:81] op_sel_hi:[1,0]
	v_pk_mul_f32 v[50:51], v[50:51], v[80:81] op_sel_hi:[1,0]
	v_mul_f32_e32 v66, v49, v49
	v_pk_fma_f32 v[66:67], v[48:49], v[48:49], v[66:67] op_sel_hi:[1,1,0]
	v_mul_f32_e32 v82, v51, v51
	v_pk_fma_f32 v[66:67], v[50:51], v[50:51], v[66:67]
	v_pk_mul_f32 v[52:53], v[52:53], v[80:81] op_sel_hi:[1,0]
	v_pk_add_f32 v[66:67], v[82:83], v[66:67] op_sel_hi:[0,1]
	v_pk_fma_f32 v[66:67], v[52:53], v[52:53], v[66:67]
	v_mul_f32_e32 v82, v53, v53
	v_pk_add_f32 v[66:67], v[82:83], v[66:67] op_sel_hi:[0,1]
	v_pk_mul_f32 v[54:55], v[54:55], v[80:81] op_sel_hi:[1,0]
	v_pk_mul_f32 v[56:57], v[56:57], v[80:81] op_sel_hi:[1,0]
	v_pk_fma_f32 v[66:67], v[54:55], v[54:55], v[66:67]
	v_mul_f32_e32 v82, v55, v55
	v_pk_add_f32 v[66:67], v[82:83], v[66:67] op_sel_hi:[0,1]
	v_pk_fma_f32 v[66:67], v[56:57], v[56:57], v[66:67]
	v_mul_f32_e32 v82, v57, v57
	v_pk_add_f32 v[66:67], v[82:83], v[66:67] op_sel_hi:[0,1]
	v_pk_mul_f32 v[58:59], v[58:59], v[80:81] op_sel_hi:[1,0]
	v_pk_mul_f32 v[60:61], v[60:61], v[80:81] op_sel_hi:[1,0]
	v_pk_fma_f32 v[66:67], v[58:59], v[58:59], v[66:67]
	v_mul_f32_e32 v82, v59, v59
	v_pk_add_f32 v[66:67], v[82:83], v[66:67] op_sel_hi:[0,1]
	v_pk_fma_f32 v[66:67], v[60:61], v[60:61], v[66:67]
	v_mul_f32_e32 v82, v61, v61
	v_pk_add_f32 v[66:67], v[82:83], v[66:67] op_sel_hi:[0,1]
	v_pk_mul_f32 v[62:63], v[62:63], v[80:81] op_sel_hi:[1,0]
	v_pk_mul_f32 v[32:33], v[32:33], v[80:81] op_sel_hi:[1,0]
	v_pk_fma_f32 v[66:67], v[62:63], v[62:63], v[66:67]
	v_mul_f32_e32 v82, v63, v63
	v_pk_add_f32 v[66:67], v[82:83], v[66:67] op_sel_hi:[0,1]
	v_pk_fma_f32 v[66:67], v[32:33], v[32:33], v[66:67]
	v_mul_f32_e32 v82, v33, v33
	v_pk_add_f32 v[66:67], v[82:83], v[66:67] op_sel_hi:[0,1]
	v_pk_mul_f32 v[34:35], v[34:35], v[80:81] op_sel_hi:[1,0]
	v_pk_mul_f32 v[36:37], v[36:37], v[80:81] op_sel_hi:[1,0]
	v_pk_fma_f32 v[66:67], v[34:35], v[34:35], v[66:67]
	v_mul_f32_e32 v82, v35, v35
	v_pk_add_f32 v[66:67], v[82:83], v[66:67] op_sel_hi:[0,1]
	v_pk_fma_f32 v[66:67], v[36:37], v[36:37], v[66:67]
	v_mul_f32_e32 v82, v37, v37
	v_pk_add_f32 v[66:67], v[82:83], v[66:67] op_sel_hi:[0,1]
	v_pk_mul_f32 v[38:39], v[38:39], v[80:81] op_sel_hi:[1,0]
	v_pk_mul_f32 v[40:41], v[40:41], v[80:81] op_sel_hi:[1,0]
	v_pk_fma_f32 v[66:67], v[38:39], v[38:39], v[66:67]
	v_mul_f32_e32 v82, v39, v39
	v_pk_add_f32 v[66:67], v[82:83], v[66:67] op_sel_hi:[0,1]
	v_pk_fma_f32 v[66:67], v[40:41], v[40:41], v[66:67]
	v_mul_f32_e32 v82, v41, v41
	v_pk_add_f32 v[82:83], v[82:83], v[66:67] op_sel_hi:[0,1]
	v_pk_mul_f32 v[66:67], v[42:43], v[80:81] op_sel_hi:[1,0]
	v_mfma_f32_32x32x16_bf16 v[0:15], v[84:87], v[88:91], v[0:15]
	v_fma_f32 v42, v66, v66, v82
	v_fma_f32 v43, v67, v67, v83
	v_mul_f32_e32 v82, v67, v67
	v_add_f32_e64 v42, v82, v42
	v_add_f32_e64 v43, v82, v43
	v_pk_mul_f32 v[44:45], v[44:45], v[80:81] op_sel_hi:[1,0]
	s_nop 0
	v_pk_fma_f32 v[42:43], v[44:45], v[44:45], v[42:43]
	v_mul_f32_e32 v82, v45, v45
	v_pk_add_f32 v[82:83], v[82:83], v[42:43] op_sel_hi:[0,1]
	v_pk_mul_f32 v[42:43], v[46:47], v[80:81] op_sel_hi:[1,0]
	s_nop 0
	v_pk_fma_f32 v[46:47], v[42:43], v[42:43], v[82:83]
	v_mul_f32_e32 v80, v43, v43
	v_pk_add_f32 v[46:47], v[80:81], v[46:47] op_sel_hi:[0,1]
	v_mov_b32_e32 v47, v46
	s_nop 1
	v_permlane32_swap_b32_e32 v46, v47
	s_and_saveexec_b64 s[4:5], s[42:43]
	v_add_f32_e32 v46, v46, v47
	v_add_u32_e32 v47, s29, v168
	ds_write_b32 v47, v46
	s_or_b64 exec, exec, s[4:5]
	v_add_f32_e32 v46, 0, v96
	v_add_f32_e32 v46, v65, v46
	v_add_f32_e32 v46, v97, v46
	v_add_f32_e32 v46, v98, v46
	v_add_f32_e32 v46, v68, v46
	v_add_f32_e32 v46, v69, v46
	v_add_f32_e32 v46, v70, v46
	v_add_f32_e32 v46, v71, v46
	v_add_f32_e32 v46, v72, v46
	v_add_f32_e32 v46, v73, v46
	v_add_f32_e32 v46, v74, v46
	v_add_f32_e32 v46, v75, v46
; __device__ __forceinline__ float sum_x32(float x) { float a, b; swap32(x, a, b); return a + b; }
; template <int NQB> ...
;     ...
;     for (int qb = 0; qb < NQB; ++qb) { const float lt = sum_x32(lrun[qb]); const float inv = 1.0f / lt; float ss = 0.f;
; #pragma unroll
;         for (int db = 0; db < 2; ++db)
; #pragma unroll
;             for (int i = 0; i < 16; ++i) { O[qb][db][i] *= inv; ss += O[qb][db][i] * O[qb][db][i]; }
;         ss = sum_x32(ss);
;         if (hh == 0) red[h * 64 + qb * 32 + r] = ss; }
;     __syncthreads();
	v_add_f32_e32 v46, v76, v46
	v_add_f32_e32 v46, v77, v46
	v_add_f32_e32 v46, v78, v46
	v_add_f32_e32 v46, v79, v46
	v_fmac_f32_e32 v46, v164, v64
	v_mov_b32_e32 v47, v46
	s_nop 1
	v_permlane32_swap_b32_e32 v46, v47
	v_add_f32_e32 v46, v46, v47
	v_div_scale_f32 v47, s[0:1], v46, v46, 1.0
	v_rcp_f32_e32 v64, v47
	s_nop 0
	v_fma_f32 v65, -v47, v64, 1.0
	v_fmac_f32_e32 v64, v65, v64
	v_div_scale_f32 v65, vcc, 1.0, v46, 1.0
	v_mul_f32_e32 v68, v65, v64
	v_fma_f32 v69, -v47, v68, v65
	v_fmac_f32_e32 v68, v69, v64
	v_fma_f32 v47, -v47, v68, v65
	v_div_fmas_f32 v47, v47, v64, v68
	v_div_fixup_f32 v46, v47, v46, 1.0
	v_pk_mul_f32 v[16:17], v[16:17], v[46:47] op_sel_hi:[1,0]
	v_pk_mul_f32 v[18:19], v[18:19], v[46:47] op_sel_hi:[1,0]
	v_mul_f32_e32 v64, v17, v17
	v_pk_fma_f32 v[64:65], v[16:17], v[16:17], v[64:65] op_sel_hi:[1,1,0]
	v_mul_f32_e32 v68, v19, v19
	v_pk_fma_f32 v[64:65], v[18:19], v[18:19], v[64:65]
	v_pk_mul_f32 v[20:21], v[20:21], v[46:47] op_sel_hi:[1,0]
	v_pk_add_f32 v[64:65], v[68:69], v[64:65] op_sel_hi:[0,1]
	v_pk_fma_f32 v[64:65], v[20:21], v[20:21], v[64:65]
	v_mul_f32_e32 v68, v21, v21
	v_pk_add_f32 v[64:65], v[68:69], v[64:65] op_sel_hi:[0,1]
	v_pk_mul_f32 v[22:23], v[22:23], v[46:47] op_sel_hi:[1,0]
	v_pk_mul_f32 v[24:25], v[24:25], v[46:47] op_sel_hi:[1,0]
	v_pk_fma_f32 v[64:65], v[22:23], v[22:23], v[64:65]
	v_mul_f32_e32 v68, v23, v23
	v_pk_add_f32 v[64:65], v[68:69], v[64:65] op_sel_hi:[0,1]
	v_pk_fma_f32 v[64:65], v[24:25], v[24:25], v[64:65]
	v_mul_f32_e32 v68, v25, v25
	v_pk_add_f32 v[64:65], v[68:69], v[64:65] op_sel_hi:[0,1]
	v_pk_mul_f32 v[26:27], v[26:27], v[46:47] op_sel_hi:[1,0]
	v_pk_mul_f32 v[28:29], v[28:29], v[46:47] op_sel_hi:[1,0]
	v_pk_fma_f32 v[64:65], v[26:27], v[26:27], v[64:65]
	v_mul_f32_e32 v68, v27, v27
	v_pk_add_f32 v[64:65], v[68:69], v[64:65] op_sel_hi:[0,1]
	v_pk_fma_f32 v[64:65], v[28:29], v[28:29], v[64:65]
	v_mul_f32_e32 v68, v29, v29
	v_pk_add_f32 v[64:65], v[68:69], v[64:65] op_sel_hi:[0,1]
	v_pk_mul_f32 v[30:31], v[30:31], v[46:47] op_sel_hi:[1,0]
	v_pk_mul_f32 v[0:1], v[0:1], v[46:47] op_sel_hi:[1,0]
	v_pk_fma_f32 v[64:65], v[30:31], v[30:31], v[64:65]
	v_mul_f32_e32 v68, v31, v31
	v_pk_add_f32 v[64:65], v[68:69], v[64:65] op_sel_hi:[0,1]
	v_pk_fma_f32 v[64:65], v[0:1], v[0:1], v[64:65]
	v_mul_f32_e32 v68, v1, v1
	v_pk_add_f32 v[64:65], v[68:69], v[64:65] op_sel_hi:[0,1]
	v_pk_mul_f32 v[2:3], v[2:3], v[46:47] op_sel_hi:[1,0]
	v_pk_mul_f32 v[4:5], v[4:5], v[46:47] op_sel_hi:[1,0]
	v_pk_fma_f32 v[64:65], v[2:3], v[2:3], v[64:65]
	v_mul_f32_e32 v68, v3, v3
	v_pk_add_f32 v[64:65], v[68:69], v[64:65] op_sel_hi:[0,1]
	v_pk_fma_f32 v[64:65], v[4:5], v[4:5], v[64:65]
	v_mul_f32_e32 v68, v5, v5
	v_pk_add_f32 v[64:65], v[68:69], v[64:65] op_sel_hi:[0,1]
	v_pk_mul_f32 v[6:7], v[6:7], v[46:47] op_sel_hi:[1,0]
	v_pk_mul_f32 v[8:9], v[8:9], v[46:47] op_sel_hi:[1,0]
	v_pk_fma_f32 v[64:65], v[6:7], v[6:7], v[64:65]
	v_mul_f32_e32 v68, v7, v7
	v_pk_add_f32 v[64:65], v[68:69], v[64:65] op_sel_hi:[0,1]
	v_pk_fma_f32 v[64:65], v[8:9], v[8:9], v[64:65]
	v_mul_f32_e32 v68, v9, v9
	v_pk_add_f32 v[64:65], v[68:69], v[64:65] op_sel_hi:[0,1]
	v_pk_mul_f32 v[10:11], v[10:11], v[46:47] op_sel_hi:[1,0]
	v_pk_mul_f32 v[12:13], v[12:13], v[46:47] op_sel_hi:[1,0]
	v_pk_fma_f32 v[64:65], v[10:11], v[10:11], v[64:65]
	v_mul_f32_e32 v68, v11, v11
	v_pk_add_f32 v[64:65], v[68:69], v[64:65] op_sel_hi:[0,1]
	v_pk_fma_f32 v[64:65], v[12:13], v[12:13], v[64:65]
	v_mul_f32_e32 v68, v13, v13
	v_pk_add_f32 v[64:65], v[68:69], v[64:65] op_sel_hi:[0,1]
	v_pk_mul_f32 v[14:15], v[14:15], v[46:47] op_sel_hi:[1,0]
	s_nop 0
	v_pk_fma_f32 v[46:47], v[14:15], v[14:15], v[64:65]
	v_mul_f32_e32 v64, v15, v15
	v_pk_add_f32 v[46:47], v[64:65], v[46:47] op_sel_hi:[0,1]
	v_mov_b32_e32 v47, v46
	s_nop 1
	v_permlane32_swap_b32_e32 v46, v47
	s_and_saveexec_b64 s[4:5], s[42:43]
	v_add_f32_e32 v46, v46, v47
	v_add_u32_e32 v47, s29, v168
	ds_write_b32 v47, v46 offset:128
	s_or_b64 exec, exec, s[4:5]
	s_waitcnt lgkmcnt(0)
	s_barrier
; __device__ __forceinline__ unsigned pkbf(float lo, float hi) { f2_t v = {lo, hi}; return __builtin_bit_cast(unsigned, __builtin_convertvector(v, bf2_t)); }
; template <int NQB> ...
;     ...
; #pragma unroll
;     for (int qb = 0; qb < NQB; ++qb) { float tot = 0.f;
; #pragma unroll
;         for (int w = 0; w < 8; ++w) tot += red[w * 64 + qb * 32 + r];
;         const float rs = rsqrtf(tot * (1.0f / 512.0f) + EPS);
;         bf16_t* op = A3 + (size_t)(qrow0 + 32 * qb + r) * 1024 + 512 + h * 64 + 4 * hh;
; #pragma unroll
;         for (int db = 0; db < 2; ++db)
; #pragma unroll
;             for (int g = 0; g < 4; ++g) { u32x2 w; w.x = pkbf(O[qb][db][4 * g] * rs, O[qb][db][4 * g + 1] * rs); w.y = pkbf(O[qb][db][4 * g + 2] * rs, O[qb][db][4 * g + 3] * rs);
;                 *(u32x2*)(op + 32 * db + 8 * g) = w; } }
;     __syncthreads();
	ds_read2_b32 v[46:47], v170 offset1:32
	ds_read2_b32 v[64:65], v170 offset0:64 offset1:96
	ds_read2_b32 v[68:69], v170 offset0:128 offset1:160
	ds_read2_b32 v[70:71], v170 offset0:192 offset1:224
	v_add_u32_e32 v78, 0x400, v170
	s_waitcnt lgkmcnt(3)
	v_mov_b32_e32 v80, v47
	v_mov_b32_e32 v81, v46
	v_pk_add_f32 v[46:47], v[80:81], 0 op_sel_hi:[1,0]
	s_waitcnt lgkmcnt(2)
	v_mov_b32_e32 v80, v65
	v_mov_b32_e32 v81, v64
	ds_read2_b32 v[72:73], v78 offset1:32
	ds_read2_b32 v[74:75], v78 offset0:64 offset1:96
	ds_read2_b32 v[76:77], v78 offset0:128 offset1:160
	ds_read2_b32 v[78:79], v78 offset0:192 offset1:224
	v_pk_add_f32 v[46:47], v[46:47], v[80:81]
	s_waitcnt lgkmcnt(5)
	v_mov_b32_e32 v64, v69
	v_mov_b32_e32 v65, v68
	v_pk_add_f32 v[46:47], v[46:47], v[64:65]
	s_waitcnt lgkmcnt(4)
	v_mov_b32_e32 v64, v71
	v_mov_b32_e32 v65, v70
	v_pk_add_f32 v[46:47], v[46:47], v[64:65]
	s_waitcnt lgkmcnt(3)
	v_mov_b32_e32 v64, v73
	v_mov_b32_e32 v65, v72
	v_pk_add_f32 v[46:47], v[46:47], v[64:65]
	s_waitcnt lgkmcnt(2)
	v_mov_b32_e32 v64, v75
	v_mov_b32_e32 v65, v74
	v_pk_add_f32 v[46:47], v[46:47], v[64:65]
	s_waitcnt lgkmcnt(1)
	v_mov_b32_e32 v64, v77
	v_mov_b32_e32 v65, v76
	v_pk_add_f32 v[46:47], v[46:47], v[64:65]
	s_waitcnt lgkmcnt(0)
	v_mov_b32_e32 v64, v79
	v_mov_b32_e32 v65, v78
	v_pk_add_f32 v[46:47], v[46:47], v[64:65]
	s_mov_b32 s0, 0x3b000000
	v_pk_fma_f32 v[46:47], v[46:47], s[0:1], v[134:135] op_sel_hi:[1,0,0]
	s_mov_b64 s[4:5], 0
	v_mul_f32_e32 v64, 0x4b800000, v47
	v_cmp_gt_f32_e32 vcc, s13, v47
	s_nop 1
	v_cndmask_b32_e32 v47, v47, v64, vcc
	v_rsq_f32_e32 v47, v47
	v_lshlrev_b64 v[64:65], 11, v[162:163]
	v_lshl_add_u64 v[64:65], v[140:141], 0, v[64:65]
	v_mul_f32_e32 v68, 0x45800000, v47
	v_cndmask_b32_e32 v68, v47, v68, vcc
	v_pk_mul_f32 v[32:33], v[32:33], v[68:69] op_sel_hi:[1,0]
	v_pk_mul_f32 v[34:35], v[34:35], v[68:69] op_sel_hi:[1,0]
	v_cvt_pk_bf16_f32 v32, v32, v33
	v_cvt_pk_bf16_f32 v33, v34, v35
	global_store_dwordx2 v[64:65], v[32:33], off offset:1088
	v_pk_mul_f32 v[32:33], v[36:37], v[68:69] op_sel_hi:[1,0]
	v_pk_mul_f32 v[34:35], v[38:39], v[68:69] op_sel_hi:[1,0]
	v_cvt_pk_bf16_f32 v32, v32, v33
	v_cvt_pk_bf16_f32 v33, v34, v35
	global_store_dwordx2 v[64:65], v[32:33], off offset:1104
	v_pk_mul_f32 v[32:33], v[40:41], v[68:69] op_sel_hi:[1,0]
	v_pk_mul_f32 v[34:35], v[66:67], v[68:69] op_sel_hi:[1,0]
	v_cvt_pk_bf16_f32 v32, v32, v33
	v_cvt_pk_bf16_f32 v33, v34, v35
	global_store_dwordx2 v[64:65], v[32:33], off offset:1120
	v_pk_mul_f32 v[32:33], v[44:45], v[68:69] op_sel_hi:[1,0]
	v_cmp_gt_f32_e32 vcc, s13, v46
	v_cvt_pk_bf16_f32 v32, v32, v33
	v_mul_f32_e32 v33, 0x4b800000, v46
	v_cndmask_b32_e32 v33, v46, v33, vcc
	v_rsq_f32_e32 v36, v33
	v_pk_mul_f32 v[34:35], v[42:43], v[68:69] op_sel_hi:[1,0]
	v_pk_mul_f32 v[48:49], v[48:49], v[68:69] op_sel_hi:[1,0]
	v_cvt_pk_bf16_f32 v33, v34, v35
	global_store_dwordx2 v[64:65], v[32:33], off offset:1136
	v_mul_f32_e32 v32, 0x45800000, v36
	v_cndmask_b32_e32 v32, v36, v32, vcc
	v_pk_mul_f32 v[50:51], v[50:51], v[68:69] op_sel_hi:[1,0]
	v_lshlrev_b64 v[34:35], 11, v[160:161]
	v_pk_mul_f32 v[16:17], v[16:17], v[32:33] op_sel_hi:[1,0]
	v_pk_mul_f32 v[18:19], v[18:19], v[32:33] op_sel_hi:[1,0]
	v_pk_mul_f32 v[0:1], v[0:1], v[32:33] op_sel_hi:[1,0]
	v_pk_mul_f32 v[2:3], v[2:3], v[32:33] op_sel_hi:[1,0]
	v_cvt_pk_bf16_f32 v48, v48, v49
	v_cvt_pk_bf16_f32 v49, v50, v51
	v_lshl_add_u64 v[34:35], v[140:141], 0, v[34:35]
	v_cvt_pk_bf16_f32 v16, v16, v17
	v_cvt_pk_bf16_f32 v17, v18, v19
	v_cvt_pk_bf16_f32 v0, v0, v1
	v_cvt_pk_bf16_f32 v1, v2, v3
	global_store_dwordx2 v[64:65], v[48:49], off offset:1024
	v_pk_mul_f32 v[48:49], v[52:53], v[68:69] op_sel_hi:[1,0]
	v_pk_mul_f32 v[50:51], v[54:55], v[68:69] op_sel_hi:[1,0]
	global_store_dwordx2 v[34:35], v[16:17], off offset:1024
	v_pk_mul_f32 v[16:17], v[20:21], v[32:33] op_sel_hi:[1,0]
	v_pk_mul_f32 v[18:19], v[22:23], v[32:33] op_sel_hi:[1,0]
	global_store_dwordx2 v[34:35], v[0:1], off offset:1088
	v_pk_mul_f32 v[0:1], v[4:5], v[32:33] op_sel_hi:[1,0]
	v_pk_mul_f32 v[2:3], v[6:7], v[32:33] op_sel_hi:[1,0]
	v_cvt_pk_bf16_f32 v48, v48, v49
	v_cvt_pk_bf16_f32 v49, v50, v51
	v_cvt_pk_bf16_f32 v16, v16, v17
	v_cvt_pk_bf16_f32 v17, v18, v19
	v_cvt_pk_bf16_f32 v0, v0, v1
	v_cvt_pk_bf16_f32 v1, v2, v3
	global_store_dwordx2 v[64:65], v[48:49], off offset:1040
	v_pk_mul_f32 v[48:49], v[56:57], v[68:69] op_sel_hi:[1,0]
	v_pk_mul_f32 v[50:51], v[58:59], v[68:69] op_sel_hi:[1,0]
	global_store_dwordx2 v[34:35], v[16:17], off offset:1040
	v_pk_mul_f32 v[16:17], v[24:25], v[32:33] op_sel_hi:[1,0]
	v_pk_mul_f32 v[18:19], v[26:27], v[32:33] op_sel_hi:[1,0]
	global_store_dwordx2 v[34:35], v[0:1], off offset:1104
	v_pk_mul_f32 v[0:1], v[8:9], v[32:33] op_sel_hi:[1,0]
	v_pk_mul_f32 v[2:3], v[10:11], v[32:33] op_sel_hi:[1,0]
	v_cvt_pk_bf16_f32 v48, v48, v49
	v_cvt_pk_bf16_f32 v49, v50, v51
	v_cvt_pk_bf16_f32 v16, v16, v17
	v_cvt_pk_bf16_f32 v17, v18, v19
	v_cvt_pk_bf16_f32 v0, v0, v1
	v_cvt_pk_bf16_f32 v1, v2, v3
	global_store_dwordx2 v[64:65], v[48:49], off offset:1056
	v_pk_mul_f32 v[48:49], v[60:61], v[68:69] op_sel_hi:[1,0]
	v_pk_mul_f32 v[50:51], v[62:63], v[68:69] op_sel_hi:[1,0]
	global_store_dwordx2 v[34:35], v[16:17], off offset:1056
	v_pk_mul_f32 v[16:17], v[28:29], v[32:33] op_sel_hi:[1,0]
	v_pk_mul_f32 v[18:19], v[30:31], v[32:33] op_sel_hi:[1,0]
	global_store_dwordx2 v[34:35], v[0:1], off offset:1120
	v_pk_mul_f32 v[0:1], v[12:13], v[32:33] op_sel_hi:[1,0]
	v_pk_mul_f32 v[2:3], v[14:15], v[32:33] op_sel_hi:[1,0]
	v_cvt_pk_bf16_f32 v48, v48, v49
	v_cvt_pk_bf16_f32 v49, v50, v51
	v_cvt_pk_bf16_f32 v16, v16, v17
	v_cvt_pk_bf16_f32 v17, v18, v19
	v_cvt_pk_bf16_f32 v0, v0, v1
	v_cvt_pk_bf16_f32 v1, v2, v3
	global_store_dwordx2 v[64:65], v[48:49], off offset:1072
	global_store_dwordx2 v[34:35], v[16:17], off offset:1072
	global_store_dwordx2 v[34:35], v[0:1], off offset:1136
	s_barrier
